# fox: prefetch next half-tile's key bias values (static in LDS) one tile ahead so bias init does not wait on LDS after the barrier
# speedup vs baseline: 1.0091x; 1.0036x over previous
; #define LAS __attribute__((address_space(3)))
; #define GAS __attribute__((address_space(1)))
; template <int MODE> ...
;     ...
;         *(LAS f32x4*)(cbuf + 4 * tid) = (f32x4){ex + s1, ex + s2, ex + s3, ex + s4};
;         __syncthreads();
;         cq = cbuf[q];
;     }
;     if (MODE == 1) { if (tid < 8) flags[tid] = 0u; }
;     bf16x8 qr[4];
;     { const GAS bf16_t* qp = HA + (rowbase + q) * LDH + qcol + hi * 8;
; #pragma unroll
;       for (int d0 = 0; d0 < 4; ++d0) qr[d0] = *(const GAS bf16x8*)(qp + d0 * 16); }
;     bf16x8 T0, T1, ONES;
;     if (MODE == 1) {
; #pragma unroll
;         for (int j = 0; j < 8; ++j) { const int kk = 8 * (j >> 2) + 4 * hi + (j & 3); T0[j] = (kk > r32) ? (short)0x3F80 : (short)0; T1[j] = (16 + kk > r32) ? (short)0x3F80 : (short)0; ONES[j] = (short)0x3F80; }
;     }
;     LAS unsigned long long* mlds = (LAS unsigned long long*)(lds + 45568) + (wid * 32 + r32) * 33;
;     if (MODE == 2) {
;         const GAS unsigned long long* mbp = MB + (rowbase + q) * 32 + hi * 16;
;         u32x4 mw[8];
; #pragma unroll
;         for (int i = 0; i < 8; ++i) mw[i] = *(const GAS u32x4*)(mbp + 2 * i);
; #pragma unroll
;         for (int i = 0; i < 8; ++i) { mlds[hi * 16 + 2 * i] = ((unsigned long long)mw[i].y << 32) | mw[i].x; mlds[hi * 16 + 2 * i + 1] = ((unsigned long long)mw[i].w << 32) | mw[i].z; }
;     }
;     f32x16 zero16;
; #pragma unroll
;     for (int i = 0; i < 16; ++i) zero16[i] = 0.f;
;     f32x16 o0 = zero16, o1 = zero16;
;     float m = 0.f, l = 0.f, R = 0.f; bool uns = true;
.LBB0_823:
	s_mov_b64 s[0:1], 0x300
	v_lshl_add_u64 v[22:23], v[98:99], 0, s[0:1]
	s_mov_b64 s[0:1], 0x600
	v_readlane_b32 s7, v254, 7
	v_cmp_gt_u32_e32 vcc, 32, v11
	v_lshl_add_u64 v[24:25], v[98:99], 0, s[0:1]
	s_lshl_b32 s0, s7, 8
	s_lshl_b32 s1, s6, 5
	v_cndmask_b32_e32 v19, v20, v19, vcc
	v_and_b32_e32 v26, 31, v1
	s_add_i32 s6, s1, s0
	v_add_f32_e32 v19, v19, v21
	v_or_b32_e32 v102, s6, v26
	v_sub_f32_e32 v20, v19, v17
	v_readlane_b32 s0, v252, 56
	v_pk_add_f32 v[16:17], v[16:17], v[20:21] op_sel_hi:[1,0]
	v_pk_add_f32 v[14:15], v[14:15], v[20:21] op_sel_hi:[1,0]
	v_lshl_add_u32 v19, v1, 4, 0
	v_ashrrev_i32_e32 v103, 31, v102
	v_readlane_b32 s1, v252, 57
	ds_write_b128 v19, v[14:17] offset:36864
	v_lshl_add_u64 v[100:101], s[4:5], 0, v[102:103]
	v_mov_b64_e32 v[14:15], s[0:1]
	s_movk_i32 s4, 0x1880
	v_mad_u64_u32 v[14:15], s[0:1], v100, s4, v[14:15]
	v_lshrrev_b32_e32 v11, 5, v11
	v_mad_i32_i24 v15, v101, s4, v15
	v_lshl_add_u64 v[14:15], s[2:3], 1, v[14:15]
	v_lshlrev_b32_e32 v16, 4, v11
	v_mov_b32_e32 v17, v0
	v_lshl_add_u64 v[14:15], v[14:15], 0, v[16:17]
	s_mov_b32 s0, 0x62000
	s_waitcnt lgkmcnt(0)
	s_barrier
	global_load_dwordx4 v[66:69], v[14:15], off
	global_load_dwordx4 v[70:73], v[14:15], off offset:32
	global_load_dwordx4 v[74:77], v[14:15], off offset:64
	global_load_dwordx4 v[78:81], v[14:15], off offset:96
	v_add_co_u32_e32 v14, vcc, s0, v22
	s_movk_i32 s1, 0x90
	s_nop 0
	v_addc_co_u32_e32 v15, vcc, 0, v23, vcc
	v_add_co_u32_e32 v20, vcc, s0, v24
	v_lshlrev_b32_e32 v103, 2, v11
	s_nop 0
	v_addc_co_u32_e32 v21, vcc, 0, v25, vcc
	global_load_dwordx4 v[82:85], v[14:15], off
	global_load_dwordx4 v[86:89], v[20:21], off
	v_lshl_add_u32 v14, v102, 2, 0
	ds_read_b32 v105, v14 offset:36864
	v_mul_lo_u32 v14, v18, s1
	v_add3_u32 v107, 0, v14, v10
	ds_write_b128 v107, v[2:5]
	ds_write_b128 v107, v[6:9] offset:9216
	v_lshrrev_b32_e32 v2, 2, v1
	v_and_or_b32 v2, v2, 3, v103
	v_and_b32_e32 v1, 16, v1
	v_and_b32_e32 v3, 12, v12
	v_mad_u32_u24 v2, v2, s1, 0
	v_lshlrev_b32_e32 v1, 1, v1
	v_lshlrev_b32_e32 v3, 1, v3
	v_add3_u32 v108, v2, v1, v3
	v_xor_b32_e32 v1, 32, v224
	v_add_u32_e32 v2, 64, v13
	v_cmp_lt_i32_e32 vcc, v1, v2
	s_lshl_b32 s0, s7, 2
	v_add_u32_e32 v17, 0, v16
	v_mul_u32_u24_e32 v18, 0x90, v26
	v_cndmask_b32_e32 v1, v224, v1, vcc
	v_mov_b32_e32 v14, v0
	v_mov_b32_e32 v15, v0
	s_add_i32 s8, s0, 4
	s_or_b32 s10, s0, 3
	v_lshlrev_b32_e32 v109, 2, v1
	s_add_i32 s0, 0, 0x9000
	v_mov_b32_e32 v1, v0
	v_mov_b32_e32 v2, v0
	v_mov_b32_e32 v3, v0
	v_mov_b32_e32 v4, v0
	v_mov_b32_e32 v5, v0
	v_mov_b32_e32 v6, v0
	v_mov_b32_e32 v7, v0
	v_mov_b32_e32 v8, v0
	v_mov_b32_e32 v9, v0
	v_mov_b32_e32 v10, v0
	v_mov_b32_e32 v11, v0
	v_mov_b32_e32 v12, v0
	v_mov_b32_e32 v13, v0
	v_add_u32_e32 v113, v17, v18
	v_mov_b64_e32 v[32:33], v[14:15]
	s_ashr_i32 s9, s6, 6
	v_add_u32_e32 v110, s0, v16
	v_and_b32_e32 v128, 12, v224
	v_and_b32_e32 v129, 3, v224
	v_lshlrev_b32_e32 v128, 3, v128
	v_lshl_add_u32 v128, v129, 2, v128
	v_add_u32_e32 v110, v110, v128
	ds_read_b32 v128, v110
	ds_read_b32 v129, v110 offset:128
	v_mov_b64_e32 v[30:31], v[12:13]
	v_mov_b64_e32 v[28:29], v[10:11]
	v_mov_b64_e32 v[26:27], v[8:9]
	v_mov_b64_e32 v[24:25], v[6:7]
	v_mov_b64_e32 v[22:23], v[4:5]
	v_mov_b64_e32 v[20:21], v[2:3]
	v_mov_b64_e32 v[18:19], v[0:1]
	v_mov_b64_e32 v[16:17], v[14:15]
	s_mov_b32 s13, 0
	s_add_i32 s11, s9, -1
	v_or_b32_e32 v111, 0x7b, v103
	s_mov_b64 s[0:1], -1
	v_mov_b32_e32 v112, 0
	v_mov_b64_e32 v[14:15], v[12:13]
	v_mov_b64_e32 v[12:13], v[10:11]
	v_mov_b64_e32 v[10:11], v[8:9]
	v_mov_b64_e32 v[8:9], v[6:7]
	v_mov_b64_e32 v[6:7], v[4:5]
	v_mov_b64_e32 v[4:5], v[2:3]
	v_mov_b64_e32 v[2:3], v[0:1]
	v_mov_b32_e32 v114, 0
	s_waitcnt lgkmcnt(0)
	s_barrier
.LBB0_824:
	s_add_i32 s12, s13, 2
	s_min_i32 s4, s12, s10
	s_mul_i32 s4, s4, 0x62000
	s_mov_b32 s5, 0
	v_lshl_add_u64 v[34:35], s[4:5], 0, v[98:99]
	global_load_dwordx4 v[90:93], v[34:35], off offset:768
	global_load_dwordx4 v[94:97], v[34:35], off offset:1536
	s_cmp_gt_i32 s13, s9
	s_cbranch_scc1 .LBB0_832
	ds_read_b128 v[116:119], v113
	ds_read_b128 v[120:123], v113 offset:32
	ds_read_b128 v[124:127], v113 offset:64
	ds_read_b128 v[182:185], v113 offset:96
	ds_read_b128 v[186:189], v113 offset:4608
	ds_read_b128 v[190:193], v113 offset:4640
	ds_read_b128 v[242:245], v113 offset:4672
	ds_read_b128 v[246:249], v113 offset:4704
	v_sub_f32_e32 v1, v105, v112
	s_nop 0
	v_subrev_f32_dpp v34, v128, v1 row_newbcast:0 row_mask:0xf bank_mask:0xf
	v_subrev_f32_dpp v35, v128, v1 row_newbcast:1 row_mask:0xf bank_mask:0xf
	v_subrev_f32_dpp v36, v128, v1 row_newbcast:2 row_mask:0xf bank_mask:0xf
	v_subrev_f32_dpp v37, v128, v1 row_newbcast:3 row_mask:0xf bank_mask:0xf
	v_subrev_f32_dpp v38, v128, v1 row_newbcast:4 row_mask:0xf bank_mask:0xf
	v_subrev_f32_dpp v39, v128, v1 row_newbcast:5 row_mask:0xf bank_mask:0xf
	v_subrev_f32_dpp v40, v128, v1 row_newbcast:6 row_mask:0xf bank_mask:0xf
	v_subrev_f32_dpp v41, v128, v1 row_newbcast:7 row_mask:0xf bank_mask:0xf
	v_subrev_f32_dpp v42, v128, v1 row_newbcast:8 row_mask:0xf bank_mask:0xf
	v_subrev_f32_dpp v43, v128, v1 row_newbcast:9 row_mask:0xf bank_mask:0xf
	v_subrev_f32_dpp v44, v128, v1 row_newbcast:10 row_mask:0xf bank_mask:0xf
	v_subrev_f32_dpp v45, v128, v1 row_newbcast:11 row_mask:0xf bank_mask:0xf
	v_subrev_f32_dpp v46, v128, v1 row_newbcast:12 row_mask:0xf bank_mask:0xf
	v_subrev_f32_dpp v47, v128, v1 row_newbcast:13 row_mask:0xf bank_mask:0xf
	v_subrev_f32_dpp v48, v128, v1 row_newbcast:14 row_mask:0xf bank_mask:0xf
	v_subrev_f32_dpp v49, v128, v1 row_newbcast:15 row_mask:0xf bank_mask:0xf
	s_waitcnt vmcnt(4) lgkmcnt(4)
	s_nop 0
	v_mfma_f32_32x32x16_bf16 v[34:49], v[116:119], v[66:69], v[34:49]
	v_subrev_f32_dpp v50, v129, v1 row_newbcast:0 row_mask:0xf bank_mask:0xf
	v_subrev_f32_dpp v51, v129, v1 row_newbcast:1 row_mask:0xf bank_mask:0xf
	v_subrev_f32_dpp v52, v129, v1 row_newbcast:2 row_mask:0xf bank_mask:0xf
	v_subrev_f32_dpp v53, v129, v1 row_newbcast:3 row_mask:0xf bank_mask:0xf
	s_waitcnt lgkmcnt(4)
	v_mfma_f32_32x32x16_bf16 v[34:49], v[120:123], v[70:73], v[34:49]
	v_subrev_f32_dpp v54, v129, v1 row_newbcast:4 row_mask:0xf bank_mask:0xf
	v_subrev_f32_dpp v55, v129, v1 row_newbcast:5 row_mask:0xf bank_mask:0xf
	v_subrev_f32_dpp v56, v129, v1 row_newbcast:6 row_mask:0xf bank_mask:0xf
	v_subrev_f32_dpp v57, v129, v1 row_newbcast:7 row_mask:0xf bank_mask:0xf
	s_waitcnt lgkmcnt(4)
	v_mfma_f32_32x32x16_bf16 v[34:49], v[124:127], v[74:77], v[34:49]
	v_subrev_f32_dpp v58, v129, v1 row_newbcast:8 row_mask:0xf bank_mask:0xf
	v_subrev_f32_dpp v59, v129, v1 row_newbcast:9 row_mask:0xf bank_mask:0xf
	v_subrev_f32_dpp v60, v129, v1 row_newbcast:10 row_mask:0xf bank_mask:0xf
	v_subrev_f32_dpp v61, v129, v1 row_newbcast:11 row_mask:0xf bank_mask:0xf
	s_waitcnt lgkmcnt(0)
	v_mfma_f32_32x32x16_bf16 v[34:49], v[182:185], v[78:81], v[34:49]
	v_subrev_f32_dpp v62, v129, v1 row_newbcast:12 row_mask:0xf bank_mask:0xf
	v_subrev_f32_dpp v63, v129, v1 row_newbcast:13 row_mask:0xf bank_mask:0xf
	v_subrev_f32_dpp v64, v129, v1 row_newbcast:14 row_mask:0xf bank_mask:0xf
	v_subrev_f32_dpp v65, v129, v1 row_newbcast:15 row_mask:0xf bank_mask:0xf
	s_nop 1
	v_mfma_f32_32x32x16_bf16 v[50:65], v[186:189], v[66:69], v[50:65]
	ds_read_b64_tr_b16 v[198:199], v108 offset:9216
	ds_read_b64_tr_b16 v[200:201], v108 offset:10368
	ds_read_b64_tr_b16 v[202:203], v108 offset:11520
	ds_read_b64_tr_b16 v[204:205], v108 offset:12672
	v_mfma_f32_32x32x16_bf16 v[50:65], v[190:193], v[70:73], v[50:65]
	ds_read_b64_tr_b16 v[206:207], v108 offset:13824
	ds_read_b64_tr_b16 v[208:209], v108 offset:14976
	ds_read_b64_tr_b16 v[210:211], v108 offset:16128
	ds_read_b64_tr_b16 v[212:213], v108 offset:17280
	v_mfma_f32_32x32x16_bf16 v[50:65], v[242:245], v[74:77], v[50:65]
	ds_read_b64_tr_b16 v[214:215], v108 offset:9280
	ds_read_b64_tr_b16 v[216:217], v108 offset:10432
	ds_read_b64_tr_b16 v[218:219], v108 offset:11584
	ds_read_b64_tr_b16 v[220:221], v108 offset:12736
	v_mfma_f32_32x32x16_bf16 v[50:65], v[246:249], v[78:81], v[50:65]
	ds_read_b64_tr_b16 v[234:235], v108 offset:13888
	ds_read_b64_tr_b16 v[236:237], v108 offset:15040
	ds_read_b64_tr_b16 v[238:239], v108 offset:16192
	ds_read_b64_tr_b16 v[240:241], v108 offset:17344
	s_nop 1
	ds_read_b32 v130, v110 offset:256
	ds_read_b32 v131, v110 offset:384
	s_cmp_lg_u32 s9, s13
	s_cbranch_scc1 .LBB0_827
	v_add_u32_e32 v104, 0xffffffa5, v111
	v_add_u32_e32 v1, 0xffffff85, v111
	v_cmp_le_i32_e32 vcc, v104, v102
	s_nop 7
	v_cndmask_b32_e32 v50, v232, v50, vcc
	v_cmp_lt_i32_e32 vcc, v1, v102
	s_nop 1
	v_cndmask_b32_e32 v35, v232, v35, vcc
	v_cmp_le_i32_e32 vcc, v1, v102
	v_add_u32_e32 v1, 0xffffffa6, v111
	s_nop 0
	v_cndmask_b32_e32 v34, v232, v34, vcc
	v_cmp_le_i32_e32 vcc, v1, v102
	v_add_u32_e32 v1, 0xffffff87, v111
	s_nop 0
	v_cndmask_b32_e32 v51, v232, v51, vcc
	v_cmp_le_i32_e32 vcc, v1, v102
	v_add_u32_e32 v1, 0xffffffa7, v111
	s_nop 0
	v_cndmask_b32_e32 v36, v232, v36, vcc
	v_cmp_le_i32_e32 vcc, v1, v102
	v_add_u32_e32 v1, 0xffffff88, v111
	s_nop 0
	v_cndmask_b32_e32 v52, v232, v52, vcc
	v_cmp_le_i32_e32 vcc, v1, v102
	v_add_u32_e32 v1, 0xffffffa8, v111
	s_nop 0
	v_cndmask_b32_e32 v37, v232, v37, vcc
	v_cmp_le_i32_e32 vcc, v1, v102
	v_add_u32_e32 v1, 0xffffff8d, v111
	s_nop 0
	v_cndmask_b32_e32 v53, v232, v53, vcc
	v_cmp_le_i32_e32 vcc, v1, v102
	v_add_u32_e32 v1, 0xffffffad, v111
	s_nop 0
	v_cndmask_b32_e32 v38, v232, v38, vcc
	v_cmp_le_i32_e32 vcc, v1, v102
	v_add_u32_e32 v1, 0xffffff8e, v111
	s_nop 0
	v_cndmask_b32_e32 v54, v232, v54, vcc
	v_cmp_le_i32_e32 vcc, v1, v102
	v_add_u32_e32 v1, 0xffffffae, v111
	s_nop 0
	v_cndmask_b32_e32 v39, v232, v39, vcc
	v_cmp_le_i32_e32 vcc, v1, v102
	v_add_u32_e32 v1, 0xffffff8f, v111
	s_nop 0
	v_cndmask_b32_e32 v55, v232, v55, vcc
	v_cmp_le_i32_e32 vcc, v1, v102
	v_add_u32_e32 v1, 0xffffffaf, v111
	s_nop 0
	v_cndmask_b32_e32 v40, v232, v40, vcc
	v_cmp_le_i32_e32 vcc, v1, v102
	v_add_u32_e32 v1, 0xffffff90, v111
	s_nop 0
	v_cndmask_b32_e32 v56, v232, v56, vcc
	v_cmp_le_i32_e32 vcc, v1, v102
	v_add_u32_e32 v1, 0xffffffb0, v111
	s_nop 0
	v_cndmask_b32_e32 v41, v232, v41, vcc
	v_cmp_le_i32_e32 vcc, v1, v102
	v_add_u32_e32 v1, 0xffffff95, v111
	s_nop 0
	v_cndmask_b32_e32 v57, v232, v57, vcc
	v_cmp_le_i32_e32 vcc, v1, v102
	v_add_u32_e32 v1, 0xffffffb5, v111
	s_nop 0
	v_cndmask_b32_e32 v42, v232, v42, vcc
	v_cmp_le_i32_e32 vcc, v1, v102
	v_add_u32_e32 v1, 0xffffff96, v111
	s_nop 0
	v_cndmask_b32_e32 v58, v232, v58, vcc
	v_cmp_le_i32_e32 vcc, v1, v102
	v_add_u32_e32 v1, 0xffffffb6, v111
	s_nop 0
	v_cndmask_b32_e32 v43, v232, v43, vcc
	v_cmp_le_i32_e32 vcc, v1, v102
	v_add_u32_e32 v1, 0xffffff97, v111
	s_nop 0
	v_cndmask_b32_e32 v59, v232, v59, vcc
	v_cmp_le_i32_e32 vcc, v1, v102
	v_add_u32_e32 v1, 0xffffffb7, v111
	s_nop 0
	v_cndmask_b32_e32 v44, v232, v44, vcc
	v_cmp_le_i32_e32 vcc, v1, v102
	v_add_u32_e32 v1, 0xffffff98, v111
	s_nop 0
	v_cndmask_b32_e32 v60, v232, v60, vcc
	v_cmp_le_i32_e32 vcc, v1, v102
	v_add_u32_e32 v1, 0xffffffb8, v111
	s_nop 0
	v_cndmask_b32_e32 v45, v232, v45, vcc
	v_cmp_le_i32_e32 vcc, v1, v102
	v_add_u32_e32 v1, 0xffffff9d, v111
	s_nop 0
	v_cndmask_b32_e32 v61, v232, v61, vcc
	v_cmp_le_i32_e32 vcc, v1, v102
	v_add_u32_e32 v1, 0xffffffbd, v111
	s_nop 0
	v_cndmask_b32_e32 v46, v232, v46, vcc
	v_cmp_le_i32_e32 vcc, v1, v102
	v_add_u32_e32 v1, 0xffffff9e, v111
	s_nop 0
	v_cndmask_b32_e32 v62, v232, v62, vcc
	v_cmp_le_i32_e32 vcc, v1, v102
	v_add_u32_e32 v1, 0xffffffbe, v111
	s_nop 0
	v_cndmask_b32_e32 v47, v232, v47, vcc
	v_cmp_le_i32_e32 vcc, v1, v102
	v_add_u32_e32 v1, 0xffffff9f, v111
	s_nop 0
	v_cndmask_b32_e32 v63, v232, v63, vcc
	v_cmp_le_i32_e32 vcc, v1, v102
	v_add_u32_e32 v1, 0xffffffbf, v111
	s_nop 0
	v_cndmask_b32_e32 v48, v232, v48, vcc
	v_cmp_le_i32_e32 vcc, v1, v102
	v_add_u32_e32 v1, 0xffffffa0, v111
	s_nop 0
	v_cndmask_b32_e32 v64, v232, v64, vcc
	v_cmp_le_i32_e32 vcc, v1, v102
	v_subrev_u32_e32 v1, 64, v111
	s_nop 0
	v_cndmask_b32_e32 v49, v232, v49, vcc
	v_cmp_le_i32_e32 vcc, v1, v102
	s_nop 1
	v_cndmask_b32_e32 v65, v232, v65, vcc

; #define STAGE_TILE(bufi, KR, VR) do { LAS bf16_t* Ks_ = (LAS bf16_t*)(lds + (bufi) * 18432); LAS bf16_t* Vs_ = (LAS bf16_t*)(lds + (bufi) * 18432 + 9216); \
;         *(LAS u32x4*)(Ks_ + skr * 72 + sch * 8) = KR; *(LAS u32x4*)(Vs_ + skr * 72 + sch * 8) = VR; } while (0)
; #define LOAD_TILE(KR, VR, tl) do { KR = *(const GAS u32x4*)(kg + (size_t)(tl) * 64 * LDH); VR = *(const GAS u32x4*)(vg + (size_t)(tl) * 64 * LDH); } while (0)
; template <int MODE> ...
;     ...
;         LOAD_TILE(kB, vB, TILE_OF(min(it + 3, ntiles - 1)));
;         COMPUTE_TILE(TILE_OF(it + 1), 1);
;         STAGE_TILE(0, kreg, vreg);
.LBB0_832:
	s_add_i32 s4, s13, 3
	s_min_i32 s4, s4, s10
	s_mul_i32 s4, s4, 0x62000
	s_mov_b32 s5, 0
	v_lshl_add_u64 v[34:35], s[4:5], 0, v[98:99]
	s_waitcnt vmcnt(3)
	ds_write_b128 v107, v[82:85] offset:18432
	s_waitcnt vmcnt(2)
	ds_write_b128 v107, v[86:89] offset:27648
	s_waitcnt lgkmcnt(0)
	s_barrier
	global_load_dwordx4 v[82:85], v[34:35], off offset:768
	global_load_dwordx4 v[86:89], v[34:35], off offset:1536
	s_cmp_ge_i32 s13, s9
	s_cbranch_scc1 .LBB0_840
	ds_read_b128 v[116:119], v113 offset:18432
	ds_read_b128 v[120:123], v113 offset:18464
	ds_read_b128 v[124:127], v113 offset:18496
	ds_read_b128 v[182:185], v113 offset:18528
	ds_read_b128 v[186:189], v113 offset:23040
	ds_read_b128 v[190:193], v113 offset:23072
	ds_read_b128 v[242:245], v113 offset:23104
	ds_read_b128 v[246:249], v113 offset:23136
	v_sub_f32_e32 v1, v105, v112
	s_nop 0
	v_subrev_f32_dpp v34, v130, v1 row_newbcast:0 row_mask:0xf bank_mask:0xf
	v_subrev_f32_dpp v35, v130, v1 row_newbcast:1 row_mask:0xf bank_mask:0xf
	v_subrev_f32_dpp v36, v130, v1 row_newbcast:2 row_mask:0xf bank_mask:0xf
	v_subrev_f32_dpp v37, v130, v1 row_newbcast:3 row_mask:0xf bank_mask:0xf
	v_subrev_f32_dpp v38, v130, v1 row_newbcast:4 row_mask:0xf bank_mask:0xf
	v_subrev_f32_dpp v39, v130, v1 row_newbcast:5 row_mask:0xf bank_mask:0xf
	v_subrev_f32_dpp v40, v130, v1 row_newbcast:6 row_mask:0xf bank_mask:0xf
	v_subrev_f32_dpp v41, v130, v1 row_newbcast:7 row_mask:0xf bank_mask:0xf
	v_subrev_f32_dpp v42, v130, v1 row_newbcast:8 row_mask:0xf bank_mask:0xf
	v_subrev_f32_dpp v43, v130, v1 row_newbcast:9 row_mask:0xf bank_mask:0xf
	v_subrev_f32_dpp v44, v130, v1 row_newbcast:10 row_mask:0xf bank_mask:0xf
	v_subrev_f32_dpp v45, v130, v1 row_newbcast:11 row_mask:0xf bank_mask:0xf
	v_subrev_f32_dpp v46, v130, v1 row_newbcast:12 row_mask:0xf bank_mask:0xf
	v_subrev_f32_dpp v47, v130, v1 row_newbcast:13 row_mask:0xf bank_mask:0xf
	v_subrev_f32_dpp v48, v130, v1 row_newbcast:14 row_mask:0xf bank_mask:0xf
	v_subrev_f32_dpp v49, v130, v1 row_newbcast:15 row_mask:0xf bank_mask:0xf
	s_waitcnt lgkmcnt(4)
	s_nop 0
	v_mfma_f32_32x32x16_bf16 v[34:49], v[116:119], v[66:69], v[34:49]
	v_subrev_f32_dpp v50, v131, v1 row_newbcast:0 row_mask:0xf bank_mask:0xf
	v_subrev_f32_dpp v51, v131, v1 row_newbcast:1 row_mask:0xf bank_mask:0xf
	v_subrev_f32_dpp v52, v131, v1 row_newbcast:2 row_mask:0xf bank_mask:0xf
	v_subrev_f32_dpp v53, v131, v1 row_newbcast:3 row_mask:0xf bank_mask:0xf
	s_waitcnt lgkmcnt(4)
	v_mfma_f32_32x32x16_bf16 v[34:49], v[120:123], v[70:73], v[34:49]
	v_subrev_f32_dpp v54, v131, v1 row_newbcast:4 row_mask:0xf bank_mask:0xf
	v_subrev_f32_dpp v55, v131, v1 row_newbcast:5 row_mask:0xf bank_mask:0xf
	v_subrev_f32_dpp v56, v131, v1 row_newbcast:6 row_mask:0xf bank_mask:0xf
	v_subrev_f32_dpp v57, v131, v1 row_newbcast:7 row_mask:0xf bank_mask:0xf
	s_waitcnt lgkmcnt(4)
	v_mfma_f32_32x32x16_bf16 v[34:49], v[124:127], v[74:77], v[34:49]
	v_subrev_f32_dpp v58, v131, v1 row_newbcast:8 row_mask:0xf bank_mask:0xf
	v_subrev_f32_dpp v59, v131, v1 row_newbcast:9 row_mask:0xf bank_mask:0xf
	v_subrev_f32_dpp v60, v131, v1 row_newbcast:10 row_mask:0xf bank_mask:0xf
	v_subrev_f32_dpp v61, v131, v1 row_newbcast:11 row_mask:0xf bank_mask:0xf
	s_waitcnt lgkmcnt(0)
	v_mfma_f32_32x32x16_bf16 v[34:49], v[182:185], v[78:81], v[34:49]
	v_subrev_f32_dpp v62, v131, v1 row_newbcast:12 row_mask:0xf bank_mask:0xf
	v_subrev_f32_dpp v63, v131, v1 row_newbcast:13 row_mask:0xf bank_mask:0xf
	v_subrev_f32_dpp v64, v131, v1 row_newbcast:14 row_mask:0xf bank_mask:0xf
	v_subrev_f32_dpp v65, v131, v1 row_newbcast:15 row_mask:0xf bank_mask:0xf
	s_nop 1
	v_mfma_f32_32x32x16_bf16 v[50:65], v[186:189], v[66:69], v[50:65]
	ds_read_b64_tr_b16 v[198:199], v108 offset:27648
	ds_read_b64_tr_b16 v[200:201], v108 offset:28800
	ds_read_b64_tr_b16 v[202:203], v108 offset:29952
	ds_read_b64_tr_b16 v[204:205], v108 offset:31104
	v_mfma_f32_32x32x16_bf16 v[50:65], v[190:193], v[70:73], v[50:65]
	ds_read_b64_tr_b16 v[206:207], v108 offset:32256
	ds_read_b64_tr_b16 v[208:209], v108 offset:33408
	ds_read_b64_tr_b16 v[210:211], v108 offset:34560
	ds_read_b64_tr_b16 v[212:213], v108 offset:35712
	v_mfma_f32_32x32x16_bf16 v[50:65], v[242:245], v[74:77], v[50:65]
	ds_read_b64_tr_b16 v[214:215], v108 offset:27712
	ds_read_b64_tr_b16 v[216:217], v108 offset:28864
	ds_read_b64_tr_b16 v[218:219], v108 offset:30016
	ds_read_b64_tr_b16 v[220:221], v108 offset:31168
	v_mfma_f32_32x32x16_bf16 v[50:65], v[246:249], v[78:81], v[50:65]
	ds_read_b64_tr_b16 v[234:235], v108 offset:32320
	ds_read_b64_tr_b16 v[236:237], v108 offset:33472
	ds_read_b64_tr_b16 v[238:239], v108 offset:34624
	ds_read_b64_tr_b16 v[240:241], v108 offset:35776
	s_nop 1
	ds_read_b32 v128, v110 offset:512
	ds_read_b32 v129, v110 offset:640
	s_cmp_lg_u32 s11, s13
	s_cbranch_scc1 .LBB0_835
	v_subrev_u32_e32 v104, 27, v111
	v_subrev_u32_e32 v1, 59, v111
	v_cmp_le_i32_e32 vcc, v104, v102
	s_nop 7
	v_cndmask_b32_e32 v50, v232, v50, vcc
	v_cmp_lt_i32_e32 vcc, v1, v102
	s_nop 1
	v_cndmask_b32_e32 v35, v232, v35, vcc
	v_cmp_le_i32_e32 vcc, v1, v102
	v_subrev_u32_e32 v1, 26, v111
	s_nop 0
	v_cndmask_b32_e32 v34, v232, v34, vcc
	v_cmp_le_i32_e32 vcc, v1, v102
	v_subrev_u32_e32 v1, 57, v111
	s_nop 0
	v_cndmask_b32_e32 v51, v232, v51, vcc
	v_cmp_le_i32_e32 vcc, v1, v102
	v_subrev_u32_e32 v1, 25, v111
	s_nop 0
	v_cndmask_b32_e32 v36, v232, v36, vcc
	v_cmp_le_i32_e32 vcc, v1, v102
	v_subrev_u32_e32 v1, 56, v111
	s_nop 0
	v_cndmask_b32_e32 v52, v232, v52, vcc
	v_cmp_le_i32_e32 vcc, v1, v102
	v_subrev_u32_e32 v1, 24, v111
	s_nop 0
	v_cndmask_b32_e32 v37, v232, v37, vcc
	v_cmp_le_i32_e32 vcc, v1, v102
	v_subrev_u32_e32 v1, 51, v111
	s_nop 0
	v_cndmask_b32_e32 v53, v232, v53, vcc
	v_cmp_le_i32_e32 vcc, v1, v102
	v_subrev_u32_e32 v1, 19, v111
	s_nop 0
	v_cndmask_b32_e32 v38, v232, v38, vcc
	v_cmp_le_i32_e32 vcc, v1, v102
	v_subrev_u32_e32 v1, 50, v111
	s_nop 0
	v_cndmask_b32_e32 v54, v232, v54, vcc
	v_cmp_le_i32_e32 vcc, v1, v102
	v_subrev_u32_e32 v1, 18, v111
	s_nop 0
	v_cndmask_b32_e32 v39, v232, v39, vcc
	v_cmp_le_i32_e32 vcc, v1, v102
	v_subrev_u32_e32 v1, 49, v111
	s_nop 0
	v_cndmask_b32_e32 v55, v232, v55, vcc
	v_cmp_le_i32_e32 vcc, v1, v102
	v_subrev_u32_e32 v1, 17, v111
	s_nop 0
	v_cndmask_b32_e32 v40, v232, v40, vcc
	v_cmp_le_i32_e32 vcc, v1, v102
	v_subrev_u32_e32 v1, 48, v111
	s_nop 0
	v_cndmask_b32_e32 v56, v232, v56, vcc
	v_cmp_le_i32_e32 vcc, v1, v102
	v_add_u32_e32 v1, -16, v111
	s_nop 0
	v_cndmask_b32_e32 v41, v232, v41, vcc
	v_cmp_le_i32_e32 vcc, v1, v102
	v_subrev_u32_e32 v1, 43, v111
	s_nop 0
	v_cndmask_b32_e32 v57, v232, v57, vcc
	v_cmp_le_i32_e32 vcc, v1, v102
	v_add_u32_e32 v1, -11, v111
	s_nop 0
	v_cndmask_b32_e32 v42, v232, v42, vcc
	v_cmp_le_i32_e32 vcc, v1, v102
	v_subrev_u32_e32 v1, 42, v111
	s_nop 0
	v_cndmask_b32_e32 v58, v232, v58, vcc
	v_cmp_le_i32_e32 vcc, v1, v102
	v_add_u32_e32 v1, -10, v111
	s_nop 0
	v_cndmask_b32_e32 v43, v232, v43, vcc
	v_cmp_le_i32_e32 vcc, v1, v102
	v_subrev_u32_e32 v1, 41, v111
	s_nop 0
	v_cndmask_b32_e32 v59, v232, v59, vcc
	v_cmp_le_i32_e32 vcc, v1, v102
	v_add_u32_e32 v1, -9, v111
	s_nop 0
	v_cndmask_b32_e32 v44, v232, v44, vcc
	v_cmp_le_i32_e32 vcc, v1, v102
	v_subrev_u32_e32 v1, 40, v111
	s_nop 0
	v_cndmask_b32_e32 v60, v232, v60, vcc
	v_cmp_le_i32_e32 vcc, v1, v102
	v_add_u32_e32 v1, -8, v111
	s_nop 0
	v_cndmask_b32_e32 v45, v232, v45, vcc
	v_cmp_le_i32_e32 vcc, v1, v102
	v_subrev_u32_e32 v1, 35, v111
	s_nop 0
	v_cndmask_b32_e32 v61, v232, v61, vcc
	v_cmp_le_i32_e32 vcc, v1, v102
	v_add_u32_e32 v1, -3, v111
	s_nop 0
	v_cndmask_b32_e32 v46, v232, v46, vcc
	v_cmp_le_i32_e32 vcc, v1, v102
	v_subrev_u32_e32 v1, 34, v111
	s_nop 0
	v_cndmask_b32_e32 v62, v232, v62, vcc
	v_cmp_le_i32_e32 vcc, v1, v102
	v_add_u32_e32 v1, -2, v111
	s_nop 0
	v_cndmask_b32_e32 v47, v232, v47, vcc
	v_cmp_le_i32_e32 vcc, v1, v102
	v_subrev_u32_e32 v1, 33, v111
	s_nop 0
	v_cndmask_b32_e32 v63, v232, v63, vcc
	v_cmp_le_i32_e32 vcc, v1, v102
	v_add_u32_e32 v1, -1, v111
	s_nop 0
	v_cndmask_b32_e32 v48, v232, v48, vcc
	v_cmp_le_i32_e32 vcc, v1, v102
	v_subrev_u32_e32 v1, 32, v111
	s_nop 0
	v_cndmask_b32_e32 v64, v232, v64, vcc
	v_cmp_le_i32_e32 vcc, v1, v102
	s_nop 1
	v_cndmask_b32_e32 v49, v232, v49, vcc
	v_cmp_le_i32_e32 vcc, v111, v102
	s_nop 1
	v_cndmask_b32_e32 v65, v232, v65, vcc
